# P2: half of the workgroups (cid bit3) visit their 16 items rotated by 8 so HBM-bound items overlap the other half's compute-bound items
# speedup vs baseline: 1.0099x; 1.0031x over previous
.LBB0_536:
	v_readlane_b32 s0, v246, 4
	s_cmp_lt_i32 s0, 3
	v_readlane_b32 s1, v246, 5
	s_cselect_b64 s[4:5], -1, 0
	s_and_b64 s[0:1], s[4:5], s[2:3]
	s_xor_b64 s[0:1], s[0:1], -1
	s_cmpk_gt_i32 s30, 0xfff
	s_cselect_b64 s[2:3], -1, 0
	s_or_b64 s[0:1], s[2:3], s[0:1]
	s_and_b64 vcc, exec, s[0:1]
	v_writelane_b32 v246, s20, 62
	s_nop 1
	v_writelane_b32 v245, s22, 0
	v_writelane_b32 v246, s21, 63
	v_writelane_b32 v245, s23, 1
	s_cbranch_vccnz .LBB0_577
	v_writelane_b32 v245, s4, 2
	v_cmp_gt_u32_e64 s[0:1], 64, v202
	v_and_b32_e32 v40, 63, v202
	v_writelane_b32 v245, s5, 3
	v_writelane_b32 v245, s0, 4
	v_lshrrev_b32_e32 v44, 3, v202
	v_and_b32_e32 v16, 7, v202
	v_readlane_b32 s5, v246, 0
	v_writelane_b32 v245, s1, 5
	v_sub_co_u32_e64 v2, s[0:1], v44, v16
	v_lshlrev_b32_e32 v4, 2, v40
	v_cvt_f32_u32_e32 v134, v2
	v_add_u32_e32 v137, s5, v4
	v_and_b32_e32 v2, 0x3c0, v202
	v_lshl_add_u32 v138, v2, 2, v137
	v_xor_b32_e32 v2, 0x7f, v44
	v_cvt_f32_u32_e32 v142, v2
	v_add_u32_e32 v2, 0x200, v202
	v_bfe_u32 v17, v202, 4, 2
	v_lshrrev_b32_e32 v0, 4, v202
	v_mov_b32_e32 v1, 0xfffe2000
	v_lshrrev_b32_e32 v46, 3, v2
	v_lshlrev_b32_e32 v42, 3, v17
	v_bfe_u32 v18, v202, 2, 2
	v_and_or_b32 v41, v0, 60, v1
	v_mov_b32_e32 v1, s5
	s_movk_i32 s6, 0x90
	v_sub_u32_e32 v2, 0x7f, v46
	v_or_b32_e32 v6, v42, v18
	v_lshrrev_b32_e32 v9, 5, v202
	v_cvt_f32_i32_e32 v144, v2
	v_and_b32_e32 v5, 15, v202
	v_lshrrev_b32_e32 v2, 7, v202
	v_mad_u32_u24 v8, v6, s6, v1
	v_and_b32_e32 v10, 2, v9
	v_writelane_b32 v245, s0, 6
	v_lshl_add_u32 v7, v2, 5, v8
	v_lshlrev_b32_e32 v9, 5, v10
	v_lshlrev_b32_e32 v2, 10, v2
	v_lshlrev_b32_e32 v11, 8, v17
	v_lshl_or_b32 v10, v10, 4, v5
	v_writelane_b32 v245, s1, 7
	v_or3_b32 v48, v11, v2, v10
	s_movk_i32 s0, 0x80
	v_lshrrev_b32_e32 v15, 2, v202
	v_and_b32_e32 v2, 8, v202
	v_cmp_gt_u32_e64 s[0:1], s0, v202
	v_and_or_b32 v2, v15, 16, v2
	v_lshrrev_b32_e32 v146, 3, v2
	v_writelane_b32 v245, s0, 8
	v_lshlrev_b32_e32 v2, 2, v17
	v_or_b32_e32 v13, 2, v2
	v_writelane_b32 v245, s1, 9
	v_cmp_gt_u32_e64 s[0:1], v2, v16
	v_or_b32_e32 v12, 0x80, v16
	v_and_b32_e32 v19, 0xe0, v15
	v_writelane_b32 v245, s0, 10
	v_mad_u32_u24 v11, v5, s6, v1
	v_or_b32_e32 v147, v2, v19
	v_writelane_b32 v245, s1, 11
	v_cmp_lt_u32_e64 s[0:1], v2, v16
	v_or_b32_e32 v149, 2, v147
	v_or_b32_e32 v150, 3, v147
	v_writelane_b32 v245, s0, 12
	v_or_b32_e32 v151, 16, v147
	v_or_b32_e32 v152, 17, v147
	v_writelane_b32 v245, s1, 13
	v_cmp_gt_u32_e64 s[0:1], v13, v16
	v_or_b32_e32 v13, 3, v2
	v_or_b32_e32 v153, 18, v147
	v_writelane_b32 v245, s0, 14
	v_or_b32_e32 v154, 19, v147
	v_add_u32_e32 v155, 32, v147
	v_writelane_b32 v245, s1, 15
	v_cmp_gt_u32_e64 s[0:1], v13, v16
	v_or_b32_e32 v13, 0x81, v2
	v_add_u32_e32 v156, 33, v147
	v_writelane_b32 v245, s0, 16
	v_add_u32_e32 v157, 34, v147
	v_add_u32_e32 v158, 35, v147
	v_writelane_b32 v245, s1, 17
	v_cmp_gt_u32_e64 s[0:1], v13, v12
	v_or_b32_e32 v13, 0x82, v2
	v_add_u32_e32 v159, 48, v147
	v_writelane_b32 v245, s0, 18
	v_add_u32_e32 v160, 49, v147
	v_add_u32_e32 v161, 50, v147
	v_writelane_b32 v245, s1, 19
	v_cmp_gt_u32_e64 s[0:1], v13, v12
	v_or_b32_e32 v13, 0x83, v2
	v_add_u32_e32 v162, 51, v147
	v_writelane_b32 v245, s0, 20
	v_add_u32_e32 v163, 64, v147
	v_add_u32_e32 v164, 0x41, v147
	v_writelane_b32 v245, s1, 21
	v_cmp_gt_u32_e64 s[0:1], v13, v12
	v_add_u32_e32 v165, 0x42, v147
	v_add_u32_e32 v166, 0x43, v147
	v_writelane_b32 v245, s0, 22
	v_add_u32_e32 v167, 0x50, v147
	s_waitcnt vmcnt(0)
	v_add_u32_e32 v168, 0x51, v147
	v_writelane_b32 v245, s1, 23
	s_movk_i32 s0, 0x1ff
	v_cmp_lt_u32_e64 s[0:1], s0, v202
	v_add_u32_e32 v169, 0x52, v147
	v_add_u32_e32 v170, 0x53, v147
	v_writelane_b32 v245, s0, 24
	v_add_u32_e32 v171, 0x60, v147
	v_add_u32_e32 v172, 0x61, v147
	v_writelane_b32 v245, s1, 25
	s_movk_i32 s0, 0xf0
	v_and_or_b32 v54, v15, s0, v5
	v_or_b32_e32 v5, v19, v5
	v_mad_u32_u24 v15, v5, s6, v1
	v_add_u32_e32 v5, 0x80, v54
	v_cmp_gt_u32_e32 vcc, v147, v54
	v_cmp_le_u32_e64 s[0:1], v147, v5
	s_and_b64 s[0:1], vcc, s[0:1]
	v_cmp_ge_u32_e32 vcc, v147, v54
	v_writelane_b32 v245, s0, 26
	v_add_u32_e32 v173, 0x62, v147
	v_add_u32_e32 v174, 0x63, v147
	v_writelane_b32 v245, s1, 27
	v_cmp_lt_u32_e64 s[0:1], v147, v5
	s_and_b64 s[0:1], vcc, s[0:1]
	v_cmp_gt_u32_e32 vcc, v149, v54
	v_writelane_b32 v245, s0, 28
	v_add_u32_e32 v175, 0x70, v147
	v_add_u32_e32 v176, 0x71, v147
	v_writelane_b32 v245, s1, 29
	v_cmp_le_u32_e64 s[0:1], v149, v5
	s_and_b64 s[0:1], vcc, s[0:1]
	v_cmp_gt_u32_e32 vcc, v150, v54
	v_writelane_b32 v245, s0, 30
	v_add_u32_e32 v177, 0x72, v147
	v_add_u32_e32 v178, 0x73, v147
	v_writelane_b32 v245, s1, 31
	v_cmp_le_u32_e64 s[0:1], v150, v5
	s_and_b64 s[0:1], vcc, s[0:1]
	v_cmp_gt_u32_e32 vcc, v151, v54
	v_writelane_b32 v245, s0, 32
	v_add_u32_e32 v19, 0x80, v147
	s_mov_b64 s[16:17], s[20:21]
	v_writelane_b32 v245, s1, 33
	v_cmp_le_u32_e64 s[0:1], v151, v5
	s_and_b64 s[0:1], vcc, s[0:1]
	v_cmp_gt_u32_e32 vcc, v152, v54
	v_writelane_b32 v245, s0, 34
	s_mov_b64 s[18:19], s[22:23]
	v_mov_b32_e32 v43, 0
	v_writelane_b32 v245, s1, 35
	v_cmp_le_u32_e64 s[0:1], v152, v5
	s_and_b64 s[0:1], vcc, s[0:1]
	v_cmp_gt_u32_e32 vcc, v153, v54
	v_writelane_b32 v245, s0, 36
	v_readlane_b32 s44, v246, 6
	v_or_b32_e32 v12, v2, v18
	v_writelane_b32 v245, s1, 37
	v_cmp_le_u32_e64 s[0:1], v153, v5
	s_and_b64 s[0:1], vcc, s[0:1]
	v_cmp_gt_u32_e32 vcc, v154, v54
	v_writelane_b32 v245, s0, 38
	v_readlane_b32 s45, v246, 7
	v_readlane_b32 s46, v246, 8
	v_writelane_b32 v245, s1, 39
	v_cmp_le_u32_e64 s[0:1], v154, v5
	s_and_b64 s[0:1], vcc, s[0:1]
	v_cmp_gt_u32_e32 vcc, v155, v54
	v_writelane_b32 v245, s0, 40
	v_readlane_b32 s47, v246, 9
	v_readlane_b32 s48, v246, 10
	v_writelane_b32 v245, s1, 41
	v_cmp_le_u32_e64 s[0:1], v155, v5
	s_and_b64 s[0:1], vcc, s[0:1]
	v_cmp_gt_u32_e32 vcc, v156, v54
	v_writelane_b32 v245, s0, 42
	v_readlane_b32 s49, v246, 11
	v_readlane_b32 s50, v246, 12
	v_writelane_b32 v245, s1, 43
	v_cmp_le_u32_e64 s[0:1], v156, v5
	s_and_b64 s[0:1], vcc, s[0:1]
	v_cmp_gt_u32_e32 vcc, v157, v54
	v_writelane_b32 v245, s0, 44
	v_readlane_b32 s51, v246, 13
	v_readlane_b32 s52, v246, 14
	v_writelane_b32 v245, s1, 45
	v_cmp_le_u32_e64 s[0:1], v157, v5
	s_and_b64 s[0:1], vcc, s[0:1]
	v_cmp_gt_u32_e32 vcc, v158, v54
	v_writelane_b32 v245, s0, 46
	v_readlane_b32 s53, v246, 15
	v_readlane_b32 s54, v246, 16
	v_writelane_b32 v245, s1, 47
	v_cmp_le_u32_e64 s[0:1], v158, v5
	s_and_b64 s[0:1], vcc, s[0:1]
	v_cmp_gt_u32_e32 vcc, v159, v54
	v_writelane_b32 v245, s0, 48
	v_readlane_b32 s55, v246, 17
	v_readlane_b32 s56, v246, 18
	v_writelane_b32 v245, s1, 49
	v_cmp_le_u32_e64 s[0:1], v159, v5
	s_and_b64 s[0:1], vcc, s[0:1]
	v_cmp_gt_u32_e32 vcc, v160, v54
	v_writelane_b32 v245, s0, 50
	v_readlane_b32 s57, v246, 19
	v_readlane_b32 s58, v246, 20
	v_writelane_b32 v245, s1, 51
	v_cmp_le_u32_e64 s[0:1], v160, v5
	s_and_b64 s[0:1], vcc, s[0:1]
	v_cmp_gt_u32_e32 vcc, v161, v54
	v_writelane_b32 v245, s0, 52
	v_readlane_b32 s59, v246, 21
	v_lshlrev_b32_e32 v20, 3, v40
	v_writelane_b32 v245, s1, 53
	v_cmp_le_u32_e64 s[0:1], v161, v5
	s_and_b64 s[0:1], vcc, s[0:1]
	v_cmp_gt_u32_e32 vcc, v162, v54
	v_writelane_b32 v245, s0, 54
	s_waitcnt lgkmcnt(0)
	v_mov_b32_e32 v21, v43
	v_lshrrev_b32_e32 v0, 6, v202
	v_writelane_b32 v245, s1, 55
	v_cmp_le_u32_e64 s[0:1], v162, v5
	s_and_b64 s[0:1], vcc, s[0:1]
	v_cmp_gt_u32_e32 vcc, v163, v54
	v_writelane_b32 v245, s0, 56
	v_or_b32_e32 v45, 0x8000, v0
	v_lshlrev_b32_e32 v135, 9, v0
	v_writelane_b32 v245, s1, 57
	v_cmp_le_u32_e64 s[0:1], v163, v5
	s_and_b64 s[0:1], vcc, s[0:1]
	v_cmp_gt_u32_e32 vcc, v164, v54
	v_writelane_b32 v245, s0, 58
	v_lshl_add_u32 v136, v0, 5, s5
	v_lshlrev_b32_e32 v3, 11, v0
	v_writelane_b32 v245, s1, 59
	v_cmp_le_u32_e64 s[0:1], v164, v5
	s_and_b64 s[0:1], vcc, s[0:1]
	v_cmp_gt_u32_e32 vcc, v165, v54
	v_writelane_b32 v245, s0, 60
	v_add_u32_e32 v0, 1, v0
	v_cvt_f32_u32_e32 v139, v0
	v_writelane_b32 v245, s1, 61
	v_cmp_le_u32_e64 s[0:1], v165, v5
	s_and_b64 s[0:1], vcc, s[0:1]
	v_cmp_gt_u32_e32 vcc, v166, v54
	v_writelane_b32 v245, s0, 62
	v_lshlrev_b32_e32 v0, 4, v16
	v_mad_u32_u24 v12, v12, s6, v1
	v_writelane_b32 v245, s1, 63
	v_cmp_le_u32_e64 s[0:1], v166, v5
	s_and_b64 s[0:1], vcc, s[0:1]
	v_cmp_gt_u32_e32 vcc, v167, v54
	v_writelane_b32 v244, s0, 0
	v_add_u32_e32 v141, s5, v0
	v_lshlrev_b32_e32 v6, 3, v202
	v_writelane_b32 v244, s1, 1
	v_cmp_le_u32_e64 s[0:1], v167, v5
	s_and_b64 s[0:1], vcc, s[0:1]
	v_cmp_gt_u32_e32 vcc, v168, v54
	v_writelane_b32 v244, s0, 2
	v_add_u32_e32 v14, 0x600, v202
	v_and_b32_e32 v6, 24, v6
	v_writelane_b32 v244, s1, 3
	v_cmp_le_u32_e64 s[0:1], v168, v5
	s_and_b64 s[0:1], vcc, s[0:1]
	v_cmp_gt_u32_e32 vcc, v169, v54
	v_writelane_b32 v244, s0, 4
	v_or_b32_e32 v50, 0x80, v44
	v_lshrrev_b32_e32 v52, 3, v14
	v_writelane_b32 v244, s1, 5
	v_cmp_le_u32_e64 s[0:1], v169, v5
	s_and_b64 s[0:1], vcc, s[0:1]
	v_cmp_gt_u32_e32 vcc, v170, v54
	v_writelane_b32 v244, s0, 6
	v_lshl_add_u32 v133, v16, 8, s5
	v_lshlrev_b32_e32 v140, 3, v16
	v_writelane_b32 v244, s1, 7
	v_cmp_le_u32_e64 s[0:1], v170, v5
	s_and_b64 s[0:1], vcc, s[0:1]
	v_cmp_gt_u32_e32 vcc, v171, v54
	v_writelane_b32 v244, s0, 8
	v_add_u32_e32 v8, v8, v6
	v_and_b32_e32 v10, 48, v202
	v_writelane_b32 v244, s1, 9
	v_cmp_le_u32_e64 s[0:1], v171, v5
	s_and_b64 s[0:1], vcc, s[0:1]
	v_cmp_gt_u32_e32 vcc, v172, v54
	v_writelane_b32 v244, s0, 10
	v_mul_u32_u24_e32 v13, 0x90, v50
	v_mul_u32_u24_e32 v14, 0x90, v52
	v_writelane_b32 v244, s1, 11
	v_cmp_le_u32_e64 s[0:1], v172, v5
	s_and_b64 s[0:1], vcc, s[0:1]
	v_cmp_gt_u32_e32 vcc, v173, v54
	v_writelane_b32 v244, s0, 12
	v_lshl_add_u32 v55, v202, 2, s5
	v_lshl_add_u32 v132, v44, 8, s5
	v_writelane_b32 v244, s1, 13
	v_cmp_le_u32_e64 s[0:1], v173, v5
	s_and_b64 s[0:1], vcc, s[0:1]
	v_cmp_gt_u32_e32 vcc, v174, v54
	v_writelane_b32 v244, s0, 14
	v_mul_u32_u24_e32 v143, 0x90, v44
	v_mul_u32_u24_e32 v145, 0x90, v46
	v_writelane_b32 v244, s1, 15
	v_cmp_le_u32_e64 s[0:1], v174, v5
	s_and_b64 s[0:1], vcc, s[0:1]
	v_cmp_gt_u32_e32 vcc, v175, v54
	v_writelane_b32 v244, s0, 16
	v_mov_b32_e32 v49, v43
	v_mov_b32_e32 v47, v43
	v_writelane_b32 v244, s1, 17
	v_cmp_le_u32_e64 s[0:1], v175, v5
	s_and_b64 s[0:1], vcc, s[0:1]
	v_cmp_gt_u32_e32 vcc, v176, v54
	v_writelane_b32 v244, s0, 18
	v_mov_b32_e32 v51, v43
	v_mov_b32_e32 v53, v43
	v_writelane_b32 v244, s1, 19
	v_cmp_le_u32_e64 s[0:1], v176, v5
	s_and_b64 s[0:1], vcc, s[0:1]
	v_cmp_gt_u32_e32 vcc, v177, v54
	v_writelane_b32 v244, s0, 20
	v_or_b32_e32 v148, 1, v147
	v_or_b32_e32 v179, 0x8000, v16
	v_writelane_b32 v244, s1, 21
	v_cmp_le_u32_e64 s[0:1], v177, v5
	s_and_b64 s[0:1], vcc, s[0:1]
	v_cmp_gt_u32_e32 vcc, v178, v54
	v_writelane_b32 v244, s0, 22
	v_or_b32_e32 v78, 16, v48
	v_mov_b32_e32 v79, v43
	v_writelane_b32 v244, s1, 23
	v_cmp_le_u32_e64 s[0:1], v178, v5
	s_and_b64 s[0:1], vcc, s[0:1]
	v_cmp_gt_u32_e32 vcc, v19, v54
	v_writelane_b32 v244, s0, 24
	v_add_u32_e32 v19, 0x81, v147
	v_add_u32_e32 v180, -8, v44
	v_writelane_b32 v244, s1, 25
	v_cmp_le_u32_e64 s[0:1], v147, v54
	s_and_b64 s[0:1], vcc, s[0:1]
	v_cmp_gt_u32_e32 vcc, v19, v54
	v_writelane_b32 v244, s0, 26
	v_lshl_or_b32 v181, v44, 7, v140
	v_mov_b32_e32 v183, 0x358637bd
	v_writelane_b32 v244, s1, 27
	v_cmp_le_u32_e64 s[0:1], v19, v5
	s_and_b64 s[0:1], vcc, s[0:1]
	v_add_u32_e32 v19, 0x82, v147
	v_writelane_b32 v244, s0, 28
	v_cmp_gt_u32_e32 vcc, v19, v54
	v_add_u32_e32 v184, v137, v3
	v_writelane_b32 v244, s1, 29
	v_cmp_le_u32_e64 s[0:1], v19, v5
	s_and_b64 s[0:1], vcc, s[0:1]
	v_add_u32_e32 v19, 0x83, v147
	v_writelane_b32 v244, s0, 30
	v_cmp_gt_u32_e32 vcc, v19, v54
	v_add_u32_e32 v185, v7, v6
	v_writelane_b32 v244, s1, 31
	v_cmp_le_u32_e64 s[0:1], v19, v5
	v_add_u32_e32 v19, 0x90, v147
	s_and_b64 s[34:35], vcc, s[0:1]
	v_cmp_gt_u32_e32 vcc, v19, v54
	v_cmp_le_u32_e64 s[0:1], v19, v5
	v_add_u32_e32 v19, 0x91, v147
	s_and_b64 s[20:21], vcc, s[0:1]
	v_cmp_gt_u32_e32 vcc, v19, v54
	v_cmp_le_u32_e64 s[0:1], v19, v5
	v_add_u32_e32 v19, 0x92, v147
	s_and_b64 s[22:23], vcc, s[0:1]
	v_cmp_gt_u32_e32 vcc, v19, v54
	v_cmp_le_u32_e64 s[0:1], v19, v5
	v_add_u32_e32 v19, 0x93, v147
	s_and_b64 s[2:3], vcc, s[0:1]
	v_cmp_le_u32_e64 s[0:1], v19, v5
	v_or_b32_e32 v5, v147, v18
	v_mad_u32_u24 v18, v5, s6, v1
	v_mov_b32_e32 v5, v43
	v_lshl_add_u64 v[56:57], s[54:55], 0, v[4:5]
	v_readlane_b32 s44, v246, 38
	v_readlane_b32 s48, v246, 42
	v_readlane_b32 s49, v246, 43
	v_cmp_gt_u32_e32 vcc, v19, v54
	v_readlane_b32 s50, v246, 44
	v_readlane_b32 s51, v246, 45
	s_mov_b64 s[12:13], s[48:49]
	s_and_b64 s[10:11], vcc, s[0:1]
	s_mov_b64 s[14:15], s[50:51]
	v_lshl_add_u64 v[22:23], s[18:19], 0, v[4:5]
	s_mov_b64 s[0:1], 0x190cc000
	v_lshl_add_u64 v[58:59], s[14:15], 0, v[20:21]
	v_lshl_add_u64 v[60:61], s[12:13], 0, v[20:21]
	v_lshl_add_u64 v[62:63], v[22:23], 0, s[0:1]
	v_lshl_add_u64 v[20:21], s[16:17], 0, v[20:21]
	s_mov_b64 s[0:1], 0x8600000
	v_lshl_add_u64 v[64:65], v[20:21], 0, s[0:1]
	s_add_u32 s0, s18, 0x95a4000
	s_addc_u32 s1, s19, 0
	s_add_u32 s8, s18, 0xb6a4000
	s_addc_u32 s9, s19, 0
	v_writelane_b32 v244, s0, 32
	s_add_u32 s12, s18, 0xd7a4000
	s_addc_u32 s13, s19, 0
	v_writelane_b32 v244, s1, 33
	v_lshl_add_u64 v[4:5], s[16:17], 0, v[4:5]
	s_mov_b64 s[0:1], 0x9e00000
	v_lshl_add_u64 v[66:67], v[4:5], 0, s[0:1]
	s_add_u32 s0, s18, 0xf8a4000
	s_addc_u32 s1, s19, 0
	v_writelane_b32 v244, s0, 34
	v_mov_b32_e32 v1, v43
	v_lshl_add_u64 v[4:5], s[18:19], 0, v[0:1]
	v_writelane_b32 v244, s1, 35
	s_add_u32 s0, s18, 0x119a4400
	s_addc_u32 s1, s19, 0
	v_writelane_b32 v244, s0, 36
	v_add_u32_e32 v186, v8, v9
	s_mov_b32 s33, 0x3fb8aa3b
	v_writelane_b32 v244, s1, 37
	v_writelane_b32 v244, s8, 38
	s_add_u32 s0, s18, 0x15ba4000
	v_lshlrev_b32_e32 v82, 1, v42
	v_writelane_b32 v244, s9, 39
	v_writelane_b32 v244, s12, 40
	v_lshl_add_u64 v[68:69], s[8:9], 0, v[0:1]
	v_add_u32_e32 v187, v11, v10
	v_writelane_b32 v244, s13, 41
	v_writelane_b32 v244, s0, 42
	s_addc_u32 s0, s19, 0
	v_writelane_b32 v244, s0, 43
	s_mov_b64 s[0:1], 0x8524000
	v_lshl_add_u64 v[72:73], v[4:5], 0, s[0:1]
	s_mov_b64 s[0:1], 0x8d64000
	v_lshl_add_u64 v[74:75], v[4:5], 0, s[0:1]
	s_add_u32 s0, s16, 0x8e00000
	s_addc_u32 s1, s17, 0
	v_writelane_b32 v244, s0, 44
	v_lshlrev_b32_e32 v4, 4, v17
	v_mov_b32_e32 v5, v43
	v_writelane_b32 v244, s1, 45
	s_add_u32 s0, s16, 0x9600000
	s_addc_u32 s1, s17, 0
	v_writelane_b32 v244, s0, 46
	v_lshl_add_u64 v[70:71], s[12:13], 0, v[0:1]
	v_mul_lo_u32 v1, v44, s6
	v_writelane_b32 v244, s1, 47
	s_add_u32 s0, s18, 0x6424000
	s_addc_u32 s1, s19, 0
	s_add_u32 s8, s18, 0x119a4000
	s_addc_u32 s9, s19, 0
	v_writelane_b32 v244, s8, 48
	v_add3_u32 v182, v1, v0, s5
	v_mbcnt_lo_u32_b32 v0, -1, 0
	v_writelane_b32 v244, s9, 49
	v_writelane_b32 v244, s0, 50
	v_mbcnt_hi_u32_b32 v193, -1, v0
	v_and_b32_e32 v0, 64, v193
	v_writelane_b32 v244, s1, 51
	v_lshl_add_u64 v[80:81], s[0:1], 0, v[4:5]
	s_bitcmp1_b32 s30, 3
	s_cselect_b32 s0, 0x800, 0
	s_add_i32 s30, s30, s0
	s_add_i32 s0, s30, 0xfffffe00
	s_bitcmp1_b32 s30, 0
	v_writelane_b32 v244, s0, 52
	s_cselect_b64 s[0:1], -1, 0
	v_writelane_b32 v244, s0, 54
	v_lshl_add_u64 v[76:77], s[8:9], 0, v[42:43]
	s_mov_b32 s17, 0
	v_writelane_b32 v244, s1, 55
	v_readlane_b32 s0, v246, 1
	v_readlane_b32 s1, v246, 2
	s_bitcmp1_b32 s0, 0
	s_cselect_b64 s[0:1], -1, 0
	v_writelane_b32 v244, s0, 56
	v_add_u32_e32 v188, v12, v6
	v_lshlrev_b32_e32 v84, 1, v2
	v_add_u32_e32 v189, v141, v13
	v_add_u32_e32 v190, v141, v14
	v_add_u32_e32 v191, v15, v10
	v_add_u32_e32 v192, v18, v6
	v_add_u32_e32 v194, 64, v0
	v_xor_b32_e32 v195, 1, v193
	v_xor_b32_e32 v196, 2, v193
	v_xor_b32_e32 v197, 4, v193
	v_xor_b32_e32 v198, 8, v193
	v_xor_b32_e32 v199, 16, v193
	v_xor_b32_e32 v200, 32, v193
	v_mov_b32_e32 v201, 0x42800000
	v_add_u32_e32 v203, 0x800, v133
	v_add_u32_e32 v204, 0x808, v133
	v_add_u32_e32 v205, 0x810, v133
	v_add_u32_e32 v206, 0x818, v133
	v_add_u32_e32 v207, 0x820, v133
	v_add_u32_e32 v208, 0x828, v133
	v_add_u32_e32 v209, 0x830, v133
	v_add_u32_e32 v210, 0x838, v133
	v_mov_b32_e32 v211, 0xf149f2ca
	s_mov_b32 s6, s30
	v_readlane_b32 s45, v246, 39
	v_readlane_b32 s46, v246, 40
	v_readlane_b32 s47, v246, 41
	v_readlane_b32 s52, v246, 46
	v_readlane_b32 s53, v246, 47
	v_readlane_b32 s54, v246, 48
	v_readlane_b32 s55, v246, 49
	v_readlane_b32 s56, v246, 50
	v_readlane_b32 s57, v246, 51
	v_readlane_b32 s58, v246, 52
	v_readlane_b32 s59, v246, 53
	v_writelane_b32 v244, s1, 57
	s_branch .LBB0_539
.LBB0_538:
	v_readlane_b32 s0, v246, 1
	v_readlane_b32 s1, v244, 52
	v_readlane_b32 s6, v244, 58
	s_add_i32 s1, s1, s0
	s_add_i32 s6, s6, s0
	s_cmpk_lt_i32 s6, 0x1000
	s_cbranch_scc1 .Lp2_nowrap
	s_addk_i32 s6, 0xf000
	s_addk_i32 s1, 0xf000
.Lp2_nowrap:
	s_nop 0
	v_writelane_b32 v244, s1, 52
	v_readlane_b32 s0, v244, 54
	v_readlane_b32 s4, v244, 56
	v_readlane_b32 s1, v244, 55
	v_readlane_b32 s5, v244, 57
	s_xor_b64 s[0:1], s[0:1], s[4:5]
	v_readlane_b32 s4, v246, 60
	v_writelane_b32 v244, s0, 54
	v_writelane_b32 v244, s1, 55
	s_bitcmp1_b32 s4, 3
	s_cselect_b32 s5, 0x800, 0
	s_add_i32 s4, s4, s5
	s_cmp_lg_u32 s6, s4
	s_cbranch_scc0 .LBB0_576
